# norm1 / norm2 row units: SSA-renaming hoist of every global load (x row, norm gain, shift, scale vectors) above the reduction: one latency per unit instead of six
# speedup vs baseline: 1.0177x; 1.0177x over previous
; DI int tidx() { int t = __builtin_amdgcn_workitem_id_x(); asm volatile("" : "+v"(t)); return t; }
; DI void norm_rows(KP p, int l, int which, int u, const float* xlat, const float* xctx) {
;   const int lane = tidx() & 63, w = tidx() >> 6;
;   const int row = u * 4 + w;
;   int b, t, isctx;
;   rowinfo(row, b, t, isctx);
;   const float* xr = isctx ? (xctx + (size_t)(row - MLAT) * 1024) : (xlat + (size_t)row * 1024);
;   const int ci = isctx ? 4 : b;
;   const float* mods = (const float*)(p->ws + OFF_MODS) + (size_t)(l * 5 + ci) * 6144 + which * 3072;
;   const float* g = (which ? p->norm2_g : p->norm1_g) + l * 1024;
;   f32x4 v[4];
;   float ss = 0;
; #pragma unroll
;   for (int j = 0; j < 4; ++j) {
;     v[j] = *(const f32x4*)(xr + 4 * (lane + 64 * j));
;     ss += v[j].x * v[j].x + v[j].y * v[j].y + v[j].z * v[j].z + v[j].w * v[j].w;
;   }
;   ss = wave_sum(ss);
;   const float rstd = rsqrtf(ss * (1.f / 1024.f) + EPS);
;   u16* H = (u16*)(p->ws + OFF_H) + (size_t)row * 1024;
; #pragma unroll
;   for (int j = 0; j < 4; ++j) {
;     const int c0 = 4 * (lane + 64 * j);
;     f32x4 gg = *(const f32x4*)(g + c0), sh = *(const f32x4*)(mods + c0), sc = *(const f32x4*)(mods + 1024 + c0);
.LBB0_124:
	s_or_b64 exec, exec, s[8:9]
	v_lshlrev_b32_e32 v4, 2, v4
	v_and_b32_e32 v38, 0xfc, v4
	v_lshlrev_b32_e32 v198, 2, v38
	v_lshl_add_u64 v[2:3], v[2:3], 0, v[198:199]
	s_load_dwordx2 s[10:11], s[18:19], 0x130
	s_load_dwordx2 s[8:9], s[18:19], 0x30
	global_load_dwordx4 v[14:17], v[2:3], off
	global_load_dwordx4 v[10:13], v[2:3], off offset:1024
	v_min_i32_e32 v5, 0x4000, v20
	v_ashrrev_i32_e32 v5, 12, v5
	s_mul_i32 s2, s76, 5
	v_add_u32_e32 v5, s2, v5
	v_mul_hi_i32_i24_e32 v19, 0x6000, v5
	v_mul_i32_i24_e32 v18, 0x6000, v5
	s_lshl_b64 s[2:3], s[74:75], 2
	s_waitcnt lgkmcnt(0)
	s_add_u32 s8, s8, s2
	s_mov_b32 s2, 0x800000
	s_addc_u32 s9, s9, s3
	global_load_dwordx4 v[132:135], v[2:3], off offset:2048
	s_nop 0
	global_load_dwordx4 v[136:139], v[2:3], off offset:3072
	global_load_dwordx4 v[140:143], v198, s[8:9]
	v_lshl_add_u64 v[144:145], s[10:11], 0, v[18:19]
	v_lshl_add_u64 v[146:147], v[144:145], 0, v[198:199]
	s_nop 0
	s_mov_b64 s[82:83], 0xe821000
	v_lshl_add_u64 v[148:149], v[144:145], 0, s[82:83]
	s_mov_b64 s[84:85], 0xe820000
	v_lshl_add_u64 v[150:151], v[146:147], 0, s[84:85]
	s_mov_b32 s86, 0xe820000
	v_add_co_u32_e32 v152, vcc, s86, v146
	v_lshl_add_u64 v[154:155], v[148:149], 0, v[198:199]
	s_nop 0
	v_addc_co_u32_e32 v153, vcc, 0, v147, vcc
	global_load_dwordx4 v[156:159], v[152:153], off
	global_load_dwordx4 v[160:163], v[154:155], off
	v_or_b32_e32 v164, 0x400, v198
	v_mov_b32_e32 v165, v199
	v_lshl_add_u64 v[166:167], v[148:149], 0, v[164:165]
	global_load_dwordx4 v[168:171], v198, s[8:9] offset:1024
	global_load_dwordx4 v[172:175], v[150:151], off offset:1024
	global_load_dwordx4 v[176:179], v[166:167], off
	v_or_b32_e32 v180, 0x800, v198
	v_mov_b32_e32 v181, v199
	v_lshl_add_u64 v[182:183], v[148:149], 0, v[180:181]
	global_load_dwordx4 v[184:187], v198, s[8:9] offset:2048
	global_load_dwordx4 v[188:191], v[150:151], off offset:2048
	global_load_dwordx4 v[192:195], v[182:183], off
	global_load_dwordx4 v[200:203], v198, s[8:9] offset:3072
	s_nop 0
	global_load_dwordx4 v[204:207], v[150:151], off offset:3072
	v_or_b32_e32 v196, 0xc00, v198
	v_mov_b32_e32 v197, v199
	v_lshl_add_u64 v[208:209], v[148:149], 0, v[196:197]
	global_load_dwordx4 v[224:227], v[208:209], off
	s_waitcnt vmcnt(0)
	v_lshlrev_b64 v[20:21], 11, v[20:21]
	v_mov_b32_e32 v6, v15
	v_mov_b32_e32 v7, v11
	v_mov_b32_e32 v4, v14
	v_mov_b32_e32 v5, v10
	v_pk_mul_f32 v[6:7], v[6:7], v[6:7]
	s_nop 0
	v_pk_fma_f32 v[4:5], v[4:5], v[4:5], v[6:7]
	v_mov_b32_e32 v6, v16
	v_mov_b32_e32 v7, v12
	v_pk_fma_f32 v[4:5], v[6:7], v[6:7], v[4:5]
	v_mov_b32_e32 v6, v17
	v_mov_b32_e32 v7, v13
	v_pk_fma_f32 v[22:23], v[6:7], v[6:7], v[4:5]
	v_add_f32_e32 v22, v22, v23
	v_mov_b32_e32 v26, v133
	v_mov_b32_e32 v27, v137
	v_mov_b32_e32 v24, v132
	v_mov_b32_e32 v25, v136
	v_pk_mul_f32 v[26:27], v[26:27], v[26:27]
	s_nop 0
	v_pk_fma_f32 v[24:25], v[24:25], v[24:25], v[26:27]
	v_mov_b32_e32 v26, v134
	v_mov_b32_e32 v27, v138
	v_pk_fma_f32 v[24:25], v[26:27], v[26:27], v[24:25]
	v_mov_b32_e32 v26, v135
	v_mov_b32_e32 v27, v139
	v_pk_fma_f32 v[24:25], v[26:27], v[26:27], v[24:25]
	v_add_f32_e32 v22, v22, v24
	v_add_f32_e32 v24, v22, v25
	v_and_b32_e32 v18, 64, v219
	v_add_u32_e32 v18, 64, v18
	v_xor_b32_e32 v19, 32, v219
	v_cmp_lt_i32_e32 vcc, v19, v18
	s_nop 1
	v_cndmask_b32_e32 v19, v219, v19, vcc
	v_lshlrev_b32_e32 v19, 2, v19
	ds_bpermute_b32 v19, v19, v24
	s_waitcnt lgkmcnt(0)
	v_add_f32_e32 v19, v24, v19
	v_xor_b32_e32 v24, 16, v219
	v_cmp_lt_i32_e32 vcc, v24, v18
	s_nop 1
	v_cndmask_b32_e32 v24, v219, v24, vcc
	v_lshlrev_b32_e32 v24, 2, v24
	ds_bpermute_b32 v24, v24, v19
	s_waitcnt lgkmcnt(0)
; DI unsigned pack2(float lo, float hi) { f32x2 v; v.x = lo; v.y = hi; return __builtin_bit_cast(unsigned, __builtin_convertvector(v, hwbf2)); }
; DI void norm_rows(KP p, int l, int which, int u, const float* xlat, const float* xctx) {
;     ...
;   ss = wave_sum(ss);
;   const float rstd = rsqrtf(ss * (1.f / 1024.f) + EPS);
;   u16* H = (u16*)(p->ws + OFF_H) + (size_t)row * 1024;
; #pragma unroll
;   for (int j = 0; j < 4; ++j) {
;     const int c0 = 4 * (lane + 64 * j);
;     f32x4 gg = *(const f32x4*)(g + c0), sh = *(const f32x4*)(mods + c0), sc = *(const f32x4*)(mods + 1024 + c0);
;     float o0 = v[j].x * rstd * gg.x * (1.f + sc.x) + sh.x;
;     float o1 = v[j].y * rstd * gg.y * (1.f + sc.y) + sh.y;
;     float o2 = v[j].z * rstd * gg.z * (1.f + sc.z) + sh.z;
;     float o3 = v[j].w * rstd * gg.w * (1.f + sc.w) + sh.w;
;     *(u32x2*)(H + c0) = mk2(pack2(o0, o1), pack2(o2, o3));
;   }
	v_add_f32_e32 v19, v19, v24
	v_xor_b32_e32 v24, 8, v219
	v_cmp_lt_i32_e32 vcc, v24, v18
	s_nop 1
	v_cndmask_b32_e32 v24, v219, v24, vcc
	v_lshlrev_b32_e32 v24, 2, v24
	ds_bpermute_b32 v24, v24, v19
	s_waitcnt lgkmcnt(0)
	v_add_f32_e32 v19, v19, v24
	v_xor_b32_e32 v24, 4, v219
	v_cmp_lt_i32_e32 vcc, v24, v18
	s_nop 1
	v_cndmask_b32_e32 v24, v219, v24, vcc
	v_lshlrev_b32_e32 v24, 2, v24
	ds_bpermute_b32 v24, v24, v19
	s_waitcnt lgkmcnt(0)
	v_add_f32_e32 v19, v19, v24
	v_xor_b32_e32 v24, 2, v219
	v_cmp_lt_i32_e32 vcc, v24, v18
	s_nop 1
	v_cndmask_b32_e32 v24, v219, v24, vcc
	v_lshlrev_b32_e32 v24, 2, v24
	ds_bpermute_b32 v24, v24, v19
	s_waitcnt lgkmcnt(0)
	v_add_f32_e32 v19, v19, v24
	v_xor_b32_e32 v24, 1, v219
	v_cmp_lt_i32_e32 vcc, v24, v18
	s_nop 1
	v_cndmask_b32_e32 v18, v219, v24, vcc
	v_lshlrev_b32_e32 v18, 2, v18
	ds_bpermute_b32 v18, v18, v19
	v_lshl_add_u64 v[24:25], s[10:11], 0, v[20:21]
	s_waitcnt lgkmcnt(0)
	v_add_f32_e32 v18, v19, v18
	v_mov_b32_e32 v19, 0x358637bd
	v_fmamk_f32 v18, v18, 0x3a800000, v19
	v_cmp_gt_f32_e32 vcc, s2, v18
	v_mul_f32_e32 v19, 0x4b800000, v18
	s_nop 1
	v_cndmask_b32_e32 v18, v18, v19, vcc
	v_rsq_f32_e32 v18, v18
	s_nop 1
	v_mul_f32_e32 v19, 0x45800000, v18
	s_nop 1
	v_cndmask_b32_e32 v18, v18, v19, vcc
	v_pk_mul_f32 v[14:15], v[14:15], v[18:19] op_sel_hi:[1,0]
	v_pk_mul_f32 v[14:15], v[140:141], v[14:15]
	v_pk_mul_f32 v[16:17], v[16:17], v[18:19] op_sel_hi:[1,0]
	v_pk_mul_f32 v[10:11], v[10:11], v[18:19] op_sel_hi:[1,0]
	v_pk_mul_f32 v[16:17], v[142:143], v[16:17]
	v_pk_mul_f32 v[12:13], v[12:13], v[18:19] op_sel_hi:[1,0]
	v_pk_mul_f32 v[6:7], v[132:133], v[18:19] op_sel_hi:[1,0]
	v_pk_mul_f32 v[8:9], v[134:135], v[18:19] op_sel_hi:[1,0]
	v_pk_mul_f32 v[2:3], v[136:137], v[18:19] op_sel_hi:[1,0]
	v_pk_mul_f32 v[4:5], v[138:139], v[18:19] op_sel_hi:[1,0]
	v_pk_add_f32 v[26:27], v[160:161], 1.0 op_sel_hi:[1,0]
	s_nop 0
	v_pk_fma_f32 v[14:15], v[26:27], v[14:15], v[156:157]
	v_pk_add_f32 v[26:27], v[162:163], 1.0 op_sel_hi:[1,0]
	s_nop 0
	v_pk_fma_f32 v[26:27], v[26:27], v[16:17], v[158:159]
	v_cvt_pk_bf16_f32 v16, v14, v15
	v_lshlrev_b32_e32 v14, 1, v38
	v_mov_b32_e32 v15, v199
	v_cvt_pk_bf16_f32 v17, v26, v27
	v_lshl_add_u64 v[14:15], v[24:25], 0, v[14:15]
	global_store_dwordx2 v[14:15], v[16:17], off
	v_pk_mul_f32 v[10:11], v[168:169], v[10:11]
	v_pk_mul_f32 v[12:13], v[170:171], v[12:13]
	v_pk_add_f32 v[16:17], v[176:177], 1.0 op_sel_hi:[1,0]
	s_nop 0
	v_pk_fma_f32 v[10:11], v[16:17], v[10:11], v[172:173]
	v_pk_add_f32 v[16:17], v[178:179], 1.0 op_sel_hi:[1,0]
	v_cvt_pk_bf16_f32 v10, v10, v11
	v_pk_fma_f32 v[12:13], v[16:17], v[12:13], v[174:175]
	v_cvt_pk_bf16_f32 v11, v12, v13
	global_store_dwordx2 v[14:15], v[10:11], off offset:512
	v_pk_mul_f32 v[6:7], v[184:185], v[6:7]
	v_pk_mul_f32 v[8:9], v[186:187], v[8:9]
	v_pk_add_f32 v[10:11], v[192:193], 1.0 op_sel_hi:[1,0]
	s_nop 0
	v_pk_fma_f32 v[6:7], v[6:7], v[10:11], v[188:189]
	v_pk_add_f32 v[10:11], v[194:195], 1.0 op_sel_hi:[1,0]
	v_cvt_pk_bf16_f32 v6, v6, v7
	v_pk_fma_f32 v[8:9], v[8:9], v[10:11], v[190:191]
	s_nop 0
	v_cvt_pk_bf16_f32 v7, v8, v9
	global_store_dwordx2 v[14:15], v[6:7], off offset:1024
	v_pk_mul_f32 v[2:3], v[2:3], v[200:201]
	v_pk_mul_f32 v[4:5], v[4:5], v[202:203]
	v_pk_add_f32 v[6:7], v[224:225], 1.0 op_sel_hi:[1,0]
	s_nop 0
	v_pk_fma_f32 v[2:3], v[2:3], v[6:7], v[204:205]
	v_pk_add_f32 v[6:7], v[226:227], 1.0 op_sel_hi:[1,0]
	v_cvt_pk_bf16_f32 v2, v2, v3
	v_pk_fma_f32 v[4:5], v[4:5], v[6:7], v[206:207]
	s_nop 0
	v_cvt_pk_bf16_f32 v3, v4, v5
	global_store_dwordx2 v[14:15], v[2:3], off offset:1536
	v_mov_b32_e32 v8, v202
	v_mov_b32_e32 v9, v203
	v_mov_b32_e32 v10, v204
	v_mov_b32_e32 v11, v205
	v_mov_b32_e32 v21, v225
	v_mov_b32_e32 v25, v189
	v_mov_b32_e32 v33, v177
	v_mov_b32_e32 v198, v196

; DI int tidx() { int t = __builtin_amdgcn_workitem_id_x(); asm volatile("" : "+v"(t)); return t; }
; DI void norm_rows(KP p, int l, int which, int u, const float* xlat, const float* xctx) {
;   const int lane = tidx() & 63, w = tidx() >> 6;
;   const int row = u * 4 + w;
;   int b, t, isctx;
;   rowinfo(row, b, t, isctx);
;   const float* xr = isctx ? (xctx + (size_t)(row - MLAT) * 1024) : (xlat + (size_t)row * 1024);
;   const int ci = isctx ? 4 : b;
;   const float* mods = (const float*)(p->ws + OFF_MODS) + (size_t)(l * 5 + ci) * 6144 + which * 3072;
;   const float* g = (which ? p->norm2_g : p->norm1_g) + l * 1024;
;   f32x4 v[4];
;   float ss = 0;
; #pragma unroll
;   for (int j = 0; j < 4; ++j) {
;     v[j] = *(const f32x4*)(xr + 4 * (lane + 64 * j));
;     ss += v[j].x * v[j].x + v[j].y * v[j].y + v[j].z * v[j].z + v[j].w * v[j].w;
;   }
;   ss = wave_sum(ss);
;   const float rstd = rsqrtf(ss * (1.f / 1024.f) + EPS);
;   u16* H = (u16*)(p->ws + OFF_H) + (size_t)row * 1024;
; #pragma unroll
;   for (int j = 0; j < 4; ++j) {
;     const int c0 = 4 * (lane + 64 * j);
;     f32x4 gg = *(const f32x4*)(g + c0), sh = *(const f32x4*)(mods + c0), sc = *(const f32x4*)(mods + 1024 + c0);
.LBB0_1855:
	s_or_b64 exec, exec, s[14:15]
	v_lshlrev_b32_e32 v4, 2, v4
	v_and_b32_e32 v38, 0xfc, v4
	v_lshlrev_b32_e32 v198, 2, v38
	v_lshl_add_u64 v[2:3], v[2:3], 0, v[198:199]
	s_load_dwordx2 s[14:15], s[12:13], 0x130
	v_min_i32_e32 v5, 0x4000, v24
	s_load_dwordx2 s[12:13], s[12:13], 0x38
	global_load_dwordx4 v[14:17], v[2:3], off
	global_load_dwordx4 v[10:13], v[2:3], off offset:1024
	v_ashrrev_i32_e32 v5, 12, v5
	v_readlane_b32 s16, v255, 35
	v_lshlrev_b64 v[24:25], 11, v[24:25]
	s_waitcnt lgkmcnt(0)
	v_lshl_add_u64 v[24:25], s[14:15], 0, v[24:25]
	v_add_u32_e32 v5, s16, v5
	v_mul_hi_i32_i24_e32 v19, 0x6000, v5
	v_mul_i32_i24_e32 v18, 0x6000, v5
	s_mov_b64 s[82:83], 0xe823000
	global_load_dwordx4 v[132:135], v[2:3], off offset:2048
	s_nop 0
	global_load_dwordx4 v[136:139], v[2:3], off offset:3072
	v_lshl_add_u64 v[140:141], s[14:15], 0, v[18:19]
	v_lshl_add_u64 v[142:143], v[140:141], 0, s[82:83]
	s_lshl_b64 s[84:85], s[74:75], 2
	s_mov_b64 s[86:87], 0xe824000
	s_add_u32 s88, s12, s84
	v_lshl_add_u64 v[144:145], v[140:141], 0, s[86:87]
	s_addc_u32 s89, s13, s85
	v_lshl_add_u64 v[146:147], v[142:143], 0, v[198:199]
	v_lshl_add_u64 v[148:149], v[144:145], 0, v[198:199]
	global_load_dwordx4 v[152:155], v[146:147], off
	global_load_dwordx4 v[156:159], v[148:149], off
	global_load_dwordx4 v[160:163], v198, s[88:89]
	v_or_b32_e32 v150, 0x400, v198
	v_mov_b32_e32 v151, v199
	v_lshl_add_u64 v[164:165], v[142:143], 0, v[150:151]
	v_lshl_add_u64 v[166:167], v[144:145], 0, v[150:151]
	global_load_dwordx4 v[168:171], v198, s[88:89] offset:1024
	global_load_dwordx4 v[172:175], v[166:167], off
	global_load_dwordx4 v[176:179], v[164:165], off
	v_or_b32_e32 v180, 0x800, v198
	v_mov_b32_e32 v181, v199
	v_lshl_add_u64 v[182:183], v[142:143], 0, v[180:181]
	v_lshl_add_u64 v[184:185], v[144:145], 0, v[180:181]
	global_load_dwordx4 v[188:191], v198, s[88:89] offset:2048
	global_load_dwordx4 v[192:195], v[184:185], off
	global_load_dwordx4 v[200:203], v[182:183], off
	global_load_dwordx4 v[204:207], v198, s[88:89] offset:3072
	v_or_b32_e32 v186, 0xc00, v198
	v_mov_b32_e32 v187, v199
	v_lshl_add_u64 v[196:197], v[142:143], 0, v[186:187]
	v_lshl_add_u64 v[208:209], v[144:145], 0, v[186:187]
	global_load_dwordx4 v[224:227], v[196:197], off
	global_load_dwordx4 v[236:239], v[208:209], off
	s_waitcnt vmcnt(0)
	v_mov_b32_e32 v6, v15
	v_mov_b32_e32 v7, v11
	v_mov_b32_e32 v4, v14
	v_mov_b32_e32 v5, v10
	v_pk_mul_f32 v[6:7], v[6:7], v[6:7]
	s_nop 0
	v_pk_fma_f32 v[4:5], v[4:5], v[4:5], v[6:7]
	v_mov_b32_e32 v6, v16
	v_mov_b32_e32 v7, v12
	v_pk_fma_f32 v[4:5], v[6:7], v[6:7], v[4:5]
	v_mov_b32_e32 v6, v17
	v_mov_b32_e32 v7, v13
	v_pk_fma_f32 v[20:21], v[6:7], v[6:7], v[4:5]
	v_add_f32_e32 v20, v20, v21
	v_and_b32_e32 v21, 64, v219
	v_add_u32_e32 v21, 64, v21
	v_mov_b32_e32 v26, v133
	v_mov_b32_e32 v27, v137
	v_mov_b32_e32 v22, v132
	v_mov_b32_e32 v23, v136
	v_pk_mul_f32 v[26:27], v[26:27], v[26:27]
	s_nop 0
	v_pk_fma_f32 v[22:23], v[22:23], v[22:23], v[26:27]
	v_mov_b32_e32 v26, v134
	v_mov_b32_e32 v27, v138
	v_pk_fma_f32 v[22:23], v[26:27], v[26:27], v[22:23]
	v_mov_b32_e32 v26, v135
	v_mov_b32_e32 v27, v139
	v_pk_fma_f32 v[22:23], v[26:27], v[26:27], v[22:23]
	v_xor_b32_e32 v26, 32, v219
	v_cmp_lt_i32_e32 vcc, v26, v21
	v_add_f32_e32 v20, v20, v22
	v_add_f32_e32 v20, v20, v23
	v_cndmask_b32_e32 v26, v219, v26, vcc
	v_lshlrev_b32_e32 v26, 2, v26
	ds_bpermute_b32 v26, v26, v20
	s_waitcnt lgkmcnt(0)
	v_add_f32_e32 v20, v20, v26
	v_xor_b32_e32 v26, 16, v219
	v_cmp_lt_i32_e32 vcc, v26, v21
	s_nop 1
	v_cndmask_b32_e32 v26, v219, v26, vcc
	v_lshlrev_b32_e32 v26, 2, v26
	ds_bpermute_b32 v26, v26, v20
	s_waitcnt lgkmcnt(0)
; DI unsigned pack2(float lo, float hi) { f32x2 v; v.x = lo; v.y = hi; return __builtin_bit_cast(unsigned, __builtin_convertvector(v, hwbf2)); }
; DI void norm_rows(KP p, int l, int which, int u, const float* xlat, const float* xctx) {
;     ...
;   ss = wave_sum(ss);
;   const float rstd = rsqrtf(ss * (1.f / 1024.f) + EPS);
;   u16* H = (u16*)(p->ws + OFF_H) + (size_t)row * 1024;
; #pragma unroll
;   for (int j = 0; j < 4; ++j) {
;     const int c0 = 4 * (lane + 64 * j);
;     f32x4 gg = *(const f32x4*)(g + c0), sh = *(const f32x4*)(mods + c0), sc = *(const f32x4*)(mods + 1024 + c0);
;     float o0 = v[j].x * rstd * gg.x * (1.f + sc.x) + sh.x;
;     float o1 = v[j].y * rstd * gg.y * (1.f + sc.y) + sh.y;
;     float o2 = v[j].z * rstd * gg.z * (1.f + sc.z) + sh.z;
;     float o3 = v[j].w * rstd * gg.w * (1.f + sc.w) + sh.w;
;     *(u32x2*)(H + c0) = mk2(pack2(o0, o1), pack2(o2, o3));
;   }
	v_add_f32_e32 v20, v20, v26
	v_xor_b32_e32 v26, 8, v219
	v_cmp_lt_i32_e32 vcc, v26, v21
	s_nop 1
	s_mov_b32 s16, 0x800000
	v_cndmask_b32_e32 v26, v219, v26, vcc
	v_lshlrev_b32_e32 v26, 2, v26
	ds_bpermute_b32 v26, v26, v20
	s_waitcnt lgkmcnt(0)
	v_add_f32_e32 v20, v20, v26
	v_xor_b32_e32 v26, 4, v219
	v_cmp_lt_i32_e32 vcc, v26, v21
	s_nop 1
	v_cndmask_b32_e32 v26, v219, v26, vcc
	v_lshlrev_b32_e32 v26, 2, v26
	ds_bpermute_b32 v26, v26, v20
	s_waitcnt lgkmcnt(0)
	v_add_f32_e32 v20, v20, v26
	v_xor_b32_e32 v26, 2, v219
	v_cmp_lt_i32_e32 vcc, v26, v21
	s_nop 1
	v_cndmask_b32_e32 v26, v219, v26, vcc
	v_lshlrev_b32_e32 v26, 2, v26
	ds_bpermute_b32 v26, v26, v20
	s_waitcnt lgkmcnt(0)
	v_add_f32_e32 v20, v20, v26
	v_xor_b32_e32 v26, 1, v219
	v_cmp_lt_i32_e32 vcc, v26, v21
	s_nop 1
	v_cndmask_b32_e32 v21, v219, v26, vcc
	v_lshlrev_b32_e32 v21, 2, v21
	ds_bpermute_b32 v21, v21, v20
	s_waitcnt lgkmcnt(0)
	v_add_f32_e32 v20, v20, v21
	v_mov_b32_e32 v21, 0x358637bd
	v_fmamk_f32 v20, v20, 0x3a800000, v21
	v_cmp_gt_f32_e32 vcc, s16, v20
	v_mul_f32_e32 v21, 0x4b800000, v20
	s_nop 0
	v_cndmask_b32_e32 v20, v20, v21, vcc
	v_rsq_f32_e32 v20, v20
	s_nop 0
	v_mul_f32_e32 v21, 0x45800000, v20
	v_cndmask_b32_e32 v20, v20, v21, vcc
	v_pk_mul_f32 v[14:15], v[14:15], v[20:21] op_sel_hi:[1,0]
	v_pk_mul_f32 v[16:17], v[16:17], v[20:21] op_sel_hi:[1,0]
	v_pk_mul_f32 v[10:11], v[10:11], v[20:21] op_sel_hi:[1,0]
	v_pk_mul_f32 v[12:13], v[12:13], v[20:21] op_sel_hi:[1,0]
	v_pk_mul_f32 v[6:7], v[132:133], v[20:21] op_sel_hi:[1,0]
	v_pk_mul_f32 v[8:9], v[134:135], v[20:21] op_sel_hi:[1,0]
	v_pk_mul_f32 v[2:3], v[136:137], v[20:21] op_sel_hi:[1,0]
	v_pk_mul_f32 v[4:5], v[138:139], v[20:21] op_sel_hi:[1,0]
	v_pk_mul_f32 v[14:15], v[160:161], v[14:15]
	v_pk_add_f32 v[26:27], v[156:157], 1.0 op_sel_hi:[1,0]
	v_pk_mul_f32 v[16:17], v[162:163], v[16:17]
	v_pk_fma_f32 v[14:15], v[26:27], v[14:15], v[152:153]
	v_pk_add_f32 v[26:27], v[158:159], 1.0 op_sel_hi:[1,0]
	s_nop 0
	v_pk_fma_f32 v[26:27], v[26:27], v[16:17], v[154:155]
	v_cvt_pk_bf16_f32 v16, v14, v15
	v_lshlrev_b32_e32 v14, 1, v38
	v_mov_b32_e32 v15, v199
	v_cvt_pk_bf16_f32 v17, v26, v27
	v_lshl_add_u64 v[14:15], v[24:25], 0, v[14:15]
	global_store_dwordx2 v[14:15], v[16:17], off
	v_pk_mul_f32 v[10:11], v[168:169], v[10:11]
	v_pk_add_f32 v[16:17], v[172:173], 1.0 op_sel_hi:[1,0]
	v_pk_mul_f32 v[12:13], v[170:171], v[12:13]
	v_pk_fma_f32 v[10:11], v[16:17], v[10:11], v[176:177]
	v_pk_add_f32 v[16:17], v[174:175], 1.0 op_sel_hi:[1,0]
	v_cvt_pk_bf16_f32 v10, v10, v11
	v_pk_fma_f32 v[12:13], v[16:17], v[12:13], v[178:179]
	v_cvt_pk_bf16_f32 v11, v12, v13
	global_store_dwordx2 v[14:15], v[10:11], off offset:512
	v_pk_mul_f32 v[6:7], v[188:189], v[6:7]
	v_pk_add_f32 v[10:11], v[192:193], 1.0 op_sel_hi:[1,0]
	v_pk_mul_f32 v[8:9], v[190:191], v[8:9]
	v_pk_fma_f32 v[6:7], v[6:7], v[10:11], v[200:201]
	v_pk_add_f32 v[10:11], v[194:195], 1.0 op_sel_hi:[1,0]
	v_cvt_pk_bf16_f32 v6, v6, v7
	v_pk_fma_f32 v[8:9], v[8:9], v[10:11], v[202:203]
	s_nop 0
	v_cvt_pk_bf16_f32 v7, v8, v9
	global_store_dwordx2 v[14:15], v[6:7], off offset:1024
	v_pk_mul_f32 v[2:3], v[2:3], v[204:205]
	v_pk_mul_f32 v[4:5], v[4:5], v[206:207]
	v_pk_add_f32 v[6:7], v[236:237], 1.0 op_sel_hi:[1,0]
	s_nop 0
	v_pk_fma_f32 v[2:3], v[2:3], v[6:7], v[224:225]
	v_pk_add_f32 v[6:7], v[238:239], 1.0 op_sel_hi:[1,0]
	v_cvt_pk_bf16_f32 v2, v2, v3
	v_pk_fma_f32 v[4:5], v[4:5], v[6:7], v[226:227]
	s_nop 0
	v_cvt_pk_bf16_f32 v3, v4, v5
	global_store_dwordx2 v[14:15], v[2:3], off offset:1536
	v_mov_b32_e32 v8, v206
	v_mov_b32_e32 v9, v207
	v_mov_b32_e32 v10, v224
	v_mov_b32_e32 v11, v225
	v_mov_b32_e32 v25, v201
	v_mov_b32_e32 v33, v173
	v_mov_b32_e32 v198, v186
